# mode-3 ff2 K-loop: A operand register-staged two k-tiles ahead (second staging set, loop unrolled x2) + long-branch trampolines
# speedup vs baseline: 1.0820x; 1.0099x over previous
; __global__ void __launch_bounds__(512, 2) fwd_megakernel(Params p) {
;     ...
;   for (int layer = 0; layer < 2; ++layer) {
;     const int nrows = layer == 0 ? ROWS : NLAT;
;     gemm_phase(p, layer, 0, ROWS, lds_all);
;     gbar(p, bt);
;     prep_phase(p, layer, lds);
;     gbar(p, bt);
;     mixer_phase(p, layer, lds, lds_all, &s_tile);
;     gbar(p, bt);
;     gemm_phase(p, layer, 1, nrows, lds_all);
;     gbar(p, bt);
;     ln_rows(p, p.ln1_g + layer * DM, p.ln1_b + layer * DM, nrows, layer, 3, true);
;     gbar(p, bt);
;     gemm_phase(p, layer, 2, nrows, lds_all);
;     gbar(p, bt);
;     gemm_phase(p, layer, 3, nrows, lds_all);
;     gbar(p, bt);
;     ln_rows(p, p.ln2_g + layer * DM, p.ln2_b + layer * DM, nrows, layer == 0 ? 1 : 0, 0, layer == 0);
;     if (layer == 0) gbar(p, bt);
;   }
.Ltramp_192:
	s_branch .LBB0_192

; #define G5_LOAD(k0)                                                                 \
;   {                                                                                 \
;     _Pragma("unroll") for (int i_ = 0; i_ < 4; ++i_) ra[i_] = ldg16(Ap + (size_t)(i_ * 64) * lda + (k0)); \
;     _Pragma("unroll") for (int i_ = 0; i_ < 4; ++i_) rb[i_] = ldg16(Bp + (size_t)(i_ * 64) * ldb + (k0)); \
;   }
; #define G5_STORE(s)                                                                 \
;   {                                                                                 \
;     _Pragma("unroll") for (int i_ = 0; i_ < 4; ++i_) *(u32x4*)(Sw + (s) * STG + i_ * 64 * GS) = ra[i_]; \
;     _Pragma("unroll") for (int i_ = 0; i_ < 4; ++i_) *(u32x4*)(Sw + (s) * STG + 256 * GS + i_ * 64 * GS) = rb[i_]; \
;   }
; template <typename Epi>
; DI void gemm_tile512(const u16* __restrict__ A, int lda, const u16* __restrict__ Bt, int ldb, int K, char* lds_all, Epi epi) {
;     ...
;   const int nk = K >> 6;
;   __syncthreads();
;   G5_LOAD(0);
;   G5_STORE(0);
;   G5_LOAD(64);
;   __syncthreads();
;   for (int kt = 0; kt + 2 < nk; ++kt) {
;     const int cur = kt & 1;
;     G5_COMPUTE(cur);
;     G5_STORE(cur ^ 1);
;     G5_LOAD((kt + 2) << 6);
;     __syncthreads();
;   }
.LBB0_852:
	s_lshl_b32 s15, s11, 9
	s_lshl_b32 s11, s23, 8
	s_and_b32 s11, s11, 0x100
	s_lshl_b32 s26, s10, 10
	s_lshl_b32 s10, s23, 7
	s_or_b32 s24, s11, s15
	s_sub_i32 s10, s10, s26
	s_and_b32 s25, s10, 0xffffff00
	s_mul_i32 s10, s24, 0x2100
	s_mul_hi_i32 s11, s24, 0x2100
	s_add_u32 s10, s50, s10
	s_addc_u32 s11, s51, s11
	s_mul_i32 s12, s25, 0x2100
	s_mul_hi_i32 s13, s25, 0x2100
	s_add_u32 s12, s30, s12
	s_addc_u32 s13, s31, s13
	s_mov_b64 s[98:99], s[10:11]
	s_mov_b64 s[100:101], s[12:13]
	v_lshrrev_b32_e32 v239, 3, v165
	v_and_b32_e32 v0, 7, v165
	v_mul_u32_u24_e32 v206, 0x2100, v239
	v_lshl_add_u32 v206, v0, 4, v206
	v_add_u32_e32 v207, 0x84000, v206
	v_add_u32_e32 v208, 0x108000, v206
	v_add_u32_e32 v238, 0x18c000, v206
	v_mul_u32_u24_e32 v180, 0x90, v239
	v_lshl_add_u32 v180, v0, 4, v180
	global_load_dwordx4 v[2:5], v206, s[98:99]
	global_load_dwordx4 v[6:9], v207, s[98:99]
	global_load_dwordx4 v[10:13], v208, s[98:99]
	global_load_dwordx4 v[14:17], v238, s[98:99]
	global_load_dwordx4 v[18:21], v206, s[100:101]
	global_load_dwordx4 v[22:25], v207, s[100:101]
	global_load_dwordx4 v[26:29], v208, s[100:101]
	global_load_dwordx4 v[30:33], v238, s[100:101]
	global_load_dwordx4 v[130:133], v206, s[98:99] offset:128
	global_load_dwordx4 v[134:137], v207, s[98:99] offset:128
	global_load_dwordx4 v[138:141], v208, s[98:99] offset:128
	global_load_dwordx4 v[142:145], v238, s[98:99] offset:128
	global_load_dwordx4 v[146:149], v206, s[100:101] offset:128
	global_load_dwordx4 v[150:153], v207, s[100:101] offset:128
	global_load_dwordx4 v[154:157], v208, s[100:101] offset:128
	global_load_dwordx4 v[158:161], v238, s[100:101] offset:128
	global_load_dwordx4 v[182:185], v206, s[98:99] offset:256
	global_load_dwordx4 v[186:189], v207, s[98:99] offset:256
	global_load_dwordx4 v[210:213], v208, s[98:99] offset:256
	global_load_dwordx4 v[240:243], v238, s[98:99] offset:256
	s_add_u32 s98, s98, 0x180
	s_addc_u32 s99, s99, 0
	s_add_u32 s100, s100, 0x100
	s_addc_u32 s101, s101, 0
	v_and_b32_e32 v239, 31, v165
	v_bfe_u32 v0, v165, 5, 1
	v_lshrrev_b32_e32 v179, 8, v165
	v_lshl_or_b32 v178, v179, 7, v239
	v_mul_u32_u24_e32 v178, 0x90, v178
	v_lshl_add_u32 v178, v0, 4, v178
	v_bfe_u32 v179, v165, 6, 2
	v_lshl_or_b32 v179, v179, 6, v239
	v_mul_u32_u24_e32 v179, 0x90, v179
	v_lshl_add_u32 v179, v0, 4, v179
	s_mov_b32 s14, 0x12000
	s_mov_b32 s15, 29
	s_barrier
	s_waitcnt vmcnt(19)
	ds_write_b128 v180, v[2:5]
	s_waitcnt vmcnt(18)
	ds_write_b128 v180, v[6:9] offset:9216
	s_waitcnt vmcnt(17)
	ds_write_b128 v180, v[10:13] offset:18432
	s_waitcnt vmcnt(16)
	ds_write_b128 v180, v[14:17] offset:27648
	s_waitcnt vmcnt(15)
	ds_write_b128 v180, v[18:21] offset:36864
	s_waitcnt vmcnt(14)
	ds_write_b128 v180, v[22:25] offset:46080
	s_waitcnt vmcnt(13)
	ds_write_b128 v180, v[26:29] offset:55296
	s_waitcnt vmcnt(12)
	ds_write_b128 v180, v[30:33] offset:64512
	v_add_u32_e32 v180, 0x12000, v180
	s_waitcnt lgkmcnt(0)
	s_barrier
	ds_read_b128 v[194:197], v179 offset:36864
	ds_read_b128 v[166:169], v178
	ds_read_b128 v[198:201], v179 offset:41472
	ds_read_b128 v[170:173], v178 offset:4608
	ds_read_b128 v[174:177], v178 offset:9216
	ds_read_b128 v[190:193], v178 offset:13824
	s_waitcnt lgkmcnt(4)
	v_mfma_f32_32x32x16_bf16 v[114:129], v[166:169], v[194:197], 0
	ds_read_b128 v[234:237], v179 offset:36896
	s_waitcnt lgkmcnt(4)
	v_mfma_f32_32x32x16_bf16 v[98:113], v[166:169], v[198:201], 0
	ds_read_b128 v[218:221], v178 offset:32
	s_waitcnt vmcnt(11)
	ds_write_b128 v180, v[130:133]
	global_load_dwordx4 v[130:133], v206, s[98:99]
	s_waitcnt lgkmcnt(5)
	v_mfma_f32_32x32x16_bf16 v[82:97], v[170:173], v[194:197], 0
	ds_read_b128 v[202:205], v179 offset:41504
	v_mfma_f32_32x32x16_bf16 v[66:81], v[170:173], v[198:201], 0
	ds_read_b128 v[222:225], v178 offset:4640
	s_waitcnt vmcnt(11)
	ds_write_b128 v180, v[134:137] offset:9216
	global_load_dwordx4 v[134:137], v207, s[98:99]
	s_waitcnt lgkmcnt(7)
	v_mfma_f32_32x32x16_bf16 v[50:65], v[174:177], v[194:197], 0
	ds_read_b128 v[226:229], v178 offset:9248
	v_mfma_f32_32x32x16_bf16 v[34:49], v[174:177], v[198:201], 0
	ds_read_b128 v[230:233], v178 offset:13856
	s_waitcnt vmcnt(11)
	ds_write_b128 v180, v[138:141] offset:18432
	global_load_dwordx4 v[138:141], v208, s[98:99]
	s_waitcnt lgkmcnt(9)
	v_mfma_f32_32x32x16_bf16 v[18:33], v[190:193], v[194:197], 0
	v_mfma_f32_32x32x16_bf16 v[2:17], v[190:193], v[198:201], 0
	s_waitcnt vmcnt(11)
	ds_write_b128 v180, v[142:145] offset:27648
	global_load_dwordx4 v[142:145], v238, s[98:99]
	s_waitcnt lgkmcnt(8)
	v_mfma_f32_32x32x16_bf16 v[114:129], v[218:221], v[234:237], v[114:129]
	ds_read_b128 v[194:197], v179 offset:36928
	s_waitcnt lgkmcnt(7)
	v_mfma_f32_32x32x16_bf16 v[98:113], v[218:221], v[202:205], v[98:113]
	ds_read_b128 v[166:169], v178 offset:64
	s_waitcnt vmcnt(11)
	ds_write_b128 v180, v[146:149] offset:36864
	global_load_dwordx4 v[146:149], v206, s[100:101]
	s_waitcnt lgkmcnt(8)
	v_mfma_f32_32x32x16_bf16 v[82:97], v[222:225], v[234:237], v[82:97]
	ds_read_b128 v[198:201], v179 offset:41536
	v_mfma_f32_32x32x16_bf16 v[66:81], v[222:225], v[202:205], v[66:81]
	ds_read_b128 v[170:173], v178 offset:4672
	s_waitcnt vmcnt(11)
	ds_write_b128 v180, v[150:153] offset:46080
	global_load_dwordx4 v[150:153], v207, s[100:101]
	s_waitcnt lgkmcnt(9)
	v_mfma_f32_32x32x16_bf16 v[50:65], v[226:229], v[234:237], v[50:65]
	ds_read_b128 v[174:177], v178 offset:9280
	v_mfma_f32_32x32x16_bf16 v[34:49], v[226:229], v[202:205], v[34:49]
	ds_read_b128 v[190:193], v178 offset:13888
	s_waitcnt vmcnt(11)
	ds_write_b128 v180, v[154:157] offset:55296
	global_load_dwordx4 v[154:157], v208, s[100:101]
	s_waitcnt lgkmcnt(11)
; #define G5_LOAD(k0)                                                                 \
;   {                                                                                 \
;     _Pragma("unroll") for (int i_ = 0; i_ < 4; ++i_) ra[i_] = ldg16(Ap + (size_t)(i_ * 64) * lda + (k0)); \
;     _Pragma("unroll") for (int i_ = 0; i_ < 4; ++i_) rb[i_] = ldg16(Bp + (size_t)(i_ * 64) * ldb + (k0)); \
;   }
; #define G5_STORE(s)                                                                 \
;   {                                                                                 \
;     _Pragma("unroll") for (int i_ = 0; i_ < 4; ++i_) *(u32x4*)(Sw + (s) * STG + i_ * 64 * GS) = ra[i_]; \
;     _Pragma("unroll") for (int i_ = 0; i_ < 4; ++i_) *(u32x4*)(Sw + (s) * STG + 256 * GS + i_ * 64 * GS) = rb[i_]; \
;   }
; template <typename Epi>
; DI void gemm_tile512(const u16* __restrict__ A, int lda, const u16* __restrict__ Bt, int ldb, int K, char* lds_all, Epi epi) {
;     ...
;   for (int kt = 0; kt + 2 < nk; ++kt) {
;     const int cur = kt & 1;
;     G5_COMPUTE(cur);
;     G5_STORE(cur ^ 1);
;     G5_LOAD((kt + 2) << 6);
;     __syncthreads();
;   }
	v_mfma_f32_32x32x16_bf16 v[18:33], v[230:233], v[234:237], v[18:33]
	v_mfma_f32_32x32x16_bf16 v[2:17], v[230:233], v[202:205], v[2:17]
	s_waitcnt vmcnt(11)
	ds_write_b128 v180, v[158:161] offset:64512
	global_load_dwordx4 v[158:161], v238, s[100:101]
	v_subrev_u32_e32 v180, s14, v180
	s_waitcnt lgkmcnt(8)
	v_mfma_f32_32x32x16_bf16 v[114:129], v[166:169], v[194:197], v[114:129]
	ds_read_b128 v[234:237], v179 offset:36960
	s_waitcnt lgkmcnt(7)
	v_mfma_f32_32x32x16_bf16 v[98:113], v[166:169], v[198:201], v[98:113]
	ds_read_b128 v[218:221], v178 offset:96
	s_waitcnt lgkmcnt(7)
	v_mfma_f32_32x32x16_bf16 v[82:97], v[170:173], v[194:197], v[82:97]
	ds_read_b128 v[202:205], v179 offset:41568
	v_mfma_f32_32x32x16_bf16 v[66:81], v[170:173], v[198:201], v[66:81]
	ds_read_b128 v[222:225], v178 offset:4704
	s_waitcnt lgkmcnt(7)
	v_mfma_f32_32x32x16_bf16 v[50:65], v[174:177], v[194:197], v[50:65]
	ds_read_b128 v[226:229], v178 offset:9312
	v_mfma_f32_32x32x16_bf16 v[34:49], v[174:177], v[198:201], v[34:49]
	ds_read_b128 v[230:233], v178 offset:13920
	v_add_u32_e32 v178, s14, v178
	v_add_u32_e32 v179, s14, v179
	s_waitcnt lgkmcnt(8)
	v_mfma_f32_32x32x16_bf16 v[18:33], v[190:193], v[194:197], v[18:33]
	v_mfma_f32_32x32x16_bf16 v[2:17], v[190:193], v[198:201], v[2:17]
	s_sub_u32 s14, 0, s14
	s_add_u32 s98, s98, 0x80
	s_addc_u32 s99, s99, 0
	s_add_u32 s100, s100, 0x80
	s_addc_u32 s101, s101, 0
	s_waitcnt lgkmcnt(0)
	s_barrier
	ds_read_b128 v[194:197], v179 offset:36864
	ds_read_b128 v[166:169], v178
	v_mfma_f32_32x32x16_bf16 v[114:129], v[218:221], v[234:237], v[114:129]
	ds_read_b128 v[198:201], v179 offset:41472
	v_mfma_f32_32x32x16_bf16 v[98:113], v[218:221], v[202:205], v[98:113]
	ds_read_b128 v[170:173], v178 offset:4608
	v_mfma_f32_32x32x16_bf16 v[82:97], v[222:225], v[234:237], v[82:97]
	ds_read_b128 v[174:177], v178 offset:9216
	v_mfma_f32_32x32x16_bf16 v[66:81], v[222:225], v[202:205], v[66:81]
	ds_read_b128 v[190:193], v178 offset:13824
	v_mfma_f32_32x32x16_bf16 v[50:65], v[226:229], v[234:237], v[50:65]
	v_mfma_f32_32x32x16_bf16 v[34:49], v[226:229], v[202:205], v[34:49]
	v_mfma_f32_32x32x16_bf16 v[18:33], v[230:233], v[234:237], v[18:33]
	v_mfma_f32_32x32x16_bf16 v[2:17], v[230:233], v[202:205], v[2:17]
	s_waitcnt lgkmcnt(4)
	v_mfma_f32_32x32x16_bf16 v[114:129], v[166:169], v[194:197], v[114:129]
	ds_read_b128 v[234:237], v179 offset:36896
	s_waitcnt lgkmcnt(4)
	v_mfma_f32_32x32x16_bf16 v[98:113], v[166:169], v[198:201], v[98:113]
	ds_read_b128 v[218:221], v178 offset:32
	s_waitcnt vmcnt(11)
	ds_write_b128 v180, v[182:185]
	global_load_dwordx4 v[182:185], v206, s[98:99]
	s_waitcnt lgkmcnt(5)
	v_mfma_f32_32x32x16_bf16 v[82:97], v[170:173], v[194:197], v[82:97]
	ds_read_b128 v[202:205], v179 offset:41504
	v_mfma_f32_32x32x16_bf16 v[66:81], v[170:173], v[198:201], v[66:81]
	ds_read_b128 v[222:225], v178 offset:4640
	s_waitcnt vmcnt(11)
	ds_write_b128 v180, v[186:189] offset:9216
	global_load_dwordx4 v[186:189], v207, s[98:99]
	s_waitcnt lgkmcnt(7)
	v_mfma_f32_32x32x16_bf16 v[50:65], v[174:177], v[194:197], v[50:65]
	ds_read_b128 v[226:229], v178 offset:9248
	v_mfma_f32_32x32x16_bf16 v[34:49], v[174:177], v[198:201], v[34:49]
	ds_read_b128 v[230:233], v178 offset:13856
	s_waitcnt vmcnt(11)
	ds_write_b128 v180, v[210:213] offset:18432
	global_load_dwordx4 v[210:213], v208, s[98:99]
	s_waitcnt lgkmcnt(9)
	v_mfma_f32_32x32x16_bf16 v[18:33], v[190:193], v[194:197], v[18:33]
	v_mfma_f32_32x32x16_bf16 v[2:17], v[190:193], v[198:201], v[2:17]
	s_waitcnt vmcnt(11)
	ds_write_b128 v180, v[240:243] offset:27648
	global_load_dwordx4 v[240:243], v238, s[98:99]
	s_waitcnt lgkmcnt(8)
	v_mfma_f32_32x32x16_bf16 v[114:129], v[218:221], v[234:237], v[114:129]
	ds_read_b128 v[194:197], v179 offset:36928
	s_waitcnt lgkmcnt(7)
	v_mfma_f32_32x32x16_bf16 v[98:113], v[218:221], v[202:205], v[98:113]
	ds_read_b128 v[166:169], v178 offset:64
	s_waitcnt vmcnt(7)
	ds_write_b128 v180, v[146:149] offset:36864
	global_load_dwordx4 v[146:149], v206, s[100:101]
	s_waitcnt lgkmcnt(8)
	v_mfma_f32_32x32x16_bf16 v[82:97], v[222:225], v[234:237], v[82:97]
	ds_read_b128 v[198:201], v179 offset:41536
	v_mfma_f32_32x32x16_bf16 v[66:81], v[222:225], v[202:205], v[66:81]
	ds_read_b128 v[170:173], v178 offset:4672
	s_waitcnt vmcnt(7)
	ds_write_b128 v180, v[150:153] offset:46080
	global_load_dwordx4 v[150:153], v207, s[100:101]
	s_waitcnt lgkmcnt(9)
	v_mfma_f32_32x32x16_bf16 v[50:65], v[226:229], v[234:237], v[50:65]
	ds_read_b128 v[174:177], v178 offset:9280
	v_mfma_f32_32x32x16_bf16 v[34:49], v[226:229], v[202:205], v[34:49]
	ds_read_b128 v[190:193], v178 offset:13888
	s_waitcnt vmcnt(7)
	ds_write_b128 v180, v[154:157] offset:55296
	global_load_dwordx4 v[154:157], v208, s[100:101]
	s_waitcnt lgkmcnt(11)
	v_mfma_f32_32x32x16_bf16 v[18:33], v[230:233], v[234:237], v[18:33]
	v_mfma_f32_32x32x16_bf16 v[2:17], v[230:233], v[202:205], v[2:17]
	s_waitcnt vmcnt(7)
	ds_write_b128 v180, v[158:161] offset:64512
	global_load_dwordx4 v[158:161], v238, s[100:101]
	v_subrev_u32_e32 v180, s14, v180
	s_waitcnt lgkmcnt(8)
	v_mfma_f32_32x32x16_bf16 v[114:129], v[166:169], v[194:197], v[114:129]
	ds_read_b128 v[234:237], v179 offset:36960
	s_waitcnt lgkmcnt(7)
	v_mfma_f32_32x32x16_bf16 v[98:113], v[166:169], v[198:201], v[98:113]
	ds_read_b128 v[218:221], v178 offset:96
	s_waitcnt lgkmcnt(7)
	v_mfma_f32_32x32x16_bf16 v[82:97], v[170:173], v[194:197], v[82:97]
	ds_read_b128 v[202:205], v179 offset:41568
	v_mfma_f32_32x32x16_bf16 v[66:81], v[170:173], v[198:201], v[66:81]
	ds_read_b128 v[222:225], v178 offset:4704
	s_waitcnt lgkmcnt(7)
	v_mfma_f32_32x32x16_bf16 v[50:65], v[174:177], v[194:197], v[50:65]
	ds_read_b128 v[226:229], v178 offset:9312
	v_mfma_f32_32x32x16_bf16 v[34:49], v[174:177], v[198:201], v[34:49]
	ds_read_b128 v[230:233], v178 offset:13920
	v_add_u32_e32 v178, s14, v178
	v_add_u32_e32 v179, s14, v179
	s_waitcnt lgkmcnt(8)
	v_mfma_f32_32x32x16_bf16 v[18:33], v[190:193], v[194:197], v[18:33]
	v_mfma_f32_32x32x16_bf16 v[2:17], v[190:193], v[198:201], v[2:17]
	s_sub_u32 s14, 0, s14
	s_add_u32 s98, s98, 0x80
	s_addc_u32 s99, s99, 0
	s_add_u32 s100, s100, 0x80
	s_addc_u32 s101, s101, 0
	s_waitcnt lgkmcnt(0)
; #define G5_LOAD(k0)                                                                 \
;   {                                                                                 \
;     _Pragma("unroll") for (int i_ = 0; i_ < 4; ++i_) ra[i_] = ldg16(Ap + (size_t)(i_ * 64) * lda + (k0)); \
;     _Pragma("unroll") for (int i_ = 0; i_ < 4; ++i_) rb[i_] = ldg16(Bp + (size_t)(i_ * 64) * ldb + (k0)); \
;   }
; #define G5_STORE(s)                                                                 \
;   {                                                                                 \
;     _Pragma("unroll") for (int i_ = 0; i_ < 4; ++i_) *(u32x4*)(Sw + (s) * STG + i_ * 64 * GS) = ra[i_]; \
;     _Pragma("unroll") for (int i_ = 0; i_ < 4; ++i_) *(u32x4*)(Sw + (s) * STG + 256 * GS + i_ * 64 * GS) = rb[i_]; \
;   }
; template <typename Epi>
; DI void gemm_tile512(const u16* __restrict__ A, int lda, const u16* __restrict__ Bt, int ldb, int K, char* lds_all, Epi epi) {
;     ...
;   for (int kt = 0; kt + 2 < nk; ++kt) {
;     const int cur = kt & 1;
;     G5_COMPUTE(cur);
;     G5_STORE(cur ^ 1);
;     G5_LOAD((kt + 2) << 6);
;     __syncthreads();
;   }
.Lgemm2_loop_m3:
	s_barrier
	ds_read_b128 v[194:197], v179 offset:36864
	ds_read_b128 v[166:169], v178
	v_mfma_f32_32x32x16_bf16 v[114:129], v[218:221], v[234:237], v[114:129]
	ds_read_b128 v[198:201], v179 offset:41472
	v_mfma_f32_32x32x16_bf16 v[98:113], v[218:221], v[202:205], v[98:113]
	ds_read_b128 v[170:173], v178 offset:4608
	v_mfma_f32_32x32x16_bf16 v[82:97], v[222:225], v[234:237], v[82:97]
	ds_read_b128 v[174:177], v178 offset:9216
	v_mfma_f32_32x32x16_bf16 v[66:81], v[222:225], v[202:205], v[66:81]
	ds_read_b128 v[190:193], v178 offset:13824
	v_mfma_f32_32x32x16_bf16 v[50:65], v[226:229], v[234:237], v[50:65]
	v_mfma_f32_32x32x16_bf16 v[34:49], v[226:229], v[202:205], v[34:49]
	v_mfma_f32_32x32x16_bf16 v[18:33], v[230:233], v[234:237], v[18:33]
	v_mfma_f32_32x32x16_bf16 v[2:17], v[230:233], v[202:205], v[2:17]
	s_waitcnt lgkmcnt(4)
	v_mfma_f32_32x32x16_bf16 v[114:129], v[166:169], v[194:197], v[114:129]
	ds_read_b128 v[234:237], v179 offset:36896
	s_waitcnt lgkmcnt(4)
	v_mfma_f32_32x32x16_bf16 v[98:113], v[166:169], v[198:201], v[98:113]
	ds_read_b128 v[218:221], v178 offset:32
	s_waitcnt vmcnt(15)
	ds_write_b128 v180, v[130:133]
	global_load_dwordx4 v[130:133], v206, s[98:99]
	s_waitcnt lgkmcnt(5)
	v_mfma_f32_32x32x16_bf16 v[82:97], v[170:173], v[194:197], v[82:97]
	ds_read_b128 v[202:205], v179 offset:41504
	v_mfma_f32_32x32x16_bf16 v[66:81], v[170:173], v[198:201], v[66:81]
	ds_read_b128 v[222:225], v178 offset:4640
	s_waitcnt vmcnt(15)
	ds_write_b128 v180, v[134:137] offset:9216
	global_load_dwordx4 v[134:137], v207, s[98:99]
	s_waitcnt lgkmcnt(7)
	v_mfma_f32_32x32x16_bf16 v[50:65], v[174:177], v[194:197], v[50:65]
	ds_read_b128 v[226:229], v178 offset:9248
	v_mfma_f32_32x32x16_bf16 v[34:49], v[174:177], v[198:201], v[34:49]
	ds_read_b128 v[230:233], v178 offset:13856
	s_waitcnt vmcnt(15)
	ds_write_b128 v180, v[138:141] offset:18432
	global_load_dwordx4 v[138:141], v208, s[98:99]
	s_waitcnt lgkmcnt(9)
	v_mfma_f32_32x32x16_bf16 v[18:33], v[190:193], v[194:197], v[18:33]
	v_mfma_f32_32x32x16_bf16 v[2:17], v[190:193], v[198:201], v[2:17]
	s_waitcnt vmcnt(15)
	ds_write_b128 v180, v[142:145] offset:27648
	global_load_dwordx4 v[142:145], v238, s[98:99]
	s_waitcnt lgkmcnt(8)
	v_mfma_f32_32x32x16_bf16 v[114:129], v[218:221], v[234:237], v[114:129]
	ds_read_b128 v[194:197], v179 offset:36928
	s_waitcnt lgkmcnt(7)
	v_mfma_f32_32x32x16_bf16 v[98:113], v[218:221], v[202:205], v[98:113]
	ds_read_b128 v[166:169], v178 offset:64
	s_waitcnt vmcnt(7)
	ds_write_b128 v180, v[146:149] offset:36864
	global_load_dwordx4 v[146:149], v206, s[100:101]
	s_waitcnt lgkmcnt(8)
	v_mfma_f32_32x32x16_bf16 v[82:97], v[222:225], v[234:237], v[82:97]
	ds_read_b128 v[198:201], v179 offset:41536
	v_mfma_f32_32x32x16_bf16 v[66:81], v[222:225], v[202:205], v[66:81]
	ds_read_b128 v[170:173], v178 offset:4672
	s_waitcnt vmcnt(7)
	ds_write_b128 v180, v[150:153] offset:46080
	global_load_dwordx4 v[150:153], v207, s[100:101]
	s_waitcnt lgkmcnt(9)
	v_mfma_f32_32x32x16_bf16 v[50:65], v[226:229], v[234:237], v[50:65]
	ds_read_b128 v[174:177], v178 offset:9280
	v_mfma_f32_32x32x16_bf16 v[34:49], v[226:229], v[202:205], v[34:49]
	ds_read_b128 v[190:193], v178 offset:13888
	s_waitcnt vmcnt(7)
	ds_write_b128 v180, v[154:157] offset:55296
	global_load_dwordx4 v[154:157], v208, s[100:101]
	s_waitcnt lgkmcnt(11)
	v_mfma_f32_32x32x16_bf16 v[18:33], v[230:233], v[234:237], v[18:33]
	v_mfma_f32_32x32x16_bf16 v[2:17], v[230:233], v[202:205], v[2:17]
	s_waitcnt vmcnt(7)
	ds_write_b128 v180, v[158:161] offset:64512
	global_load_dwordx4 v[158:161], v238, s[100:101]
	v_subrev_u32_e32 v180, s14, v180
	s_waitcnt lgkmcnt(8)
	v_mfma_f32_32x32x16_bf16 v[114:129], v[166:169], v[194:197], v[114:129]
	ds_read_b128 v[234:237], v179 offset:36960
	s_waitcnt lgkmcnt(7)
	v_mfma_f32_32x32x16_bf16 v[98:113], v[166:169], v[198:201], v[98:113]
	ds_read_b128 v[218:221], v178 offset:96
	s_waitcnt lgkmcnt(7)
	v_mfma_f32_32x32x16_bf16 v[82:97], v[170:173], v[194:197], v[82:97]
	ds_read_b128 v[202:205], v179 offset:41568
	v_mfma_f32_32x32x16_bf16 v[66:81], v[170:173], v[198:201], v[66:81]
	ds_read_b128 v[222:225], v178 offset:4704
	s_waitcnt lgkmcnt(7)
	v_mfma_f32_32x32x16_bf16 v[50:65], v[174:177], v[194:197], v[50:65]
	ds_read_b128 v[226:229], v178 offset:9312
	v_mfma_f32_32x32x16_bf16 v[34:49], v[174:177], v[198:201], v[34:49]
	ds_read_b128 v[230:233], v178 offset:13920
	v_add_u32_e32 v178, s14, v178
	v_add_u32_e32 v179, s14, v179
	s_waitcnt lgkmcnt(8)
	v_mfma_f32_32x32x16_bf16 v[18:33], v[190:193], v[194:197], v[18:33]
	v_mfma_f32_32x32x16_bf16 v[2:17], v[190:193], v[198:201], v[2:17]
	s_sub_u32 s14, 0, s14
	s_add_u32 s98, s98, 0x80
	s_addc_u32 s99, s99, 0
	s_add_u32 s100, s100, 0x80
	s_addc_u32 s101, s101, 0
	s_waitcnt lgkmcnt(0)
	s_barrier
; #define G5_LOAD(k0)                                                                 \
;   {                                                                                 \
;     _Pragma("unroll") for (int i_ = 0; i_ < 4; ++i_) ra[i_] = ldg16(Ap + (size_t)(i_ * 64) * lda + (k0)); \
;     _Pragma("unroll") for (int i_ = 0; i_ < 4; ++i_) rb[i_] = ldg16(Bp + (size_t)(i_ * 64) * ldb + (k0)); \
;   }
; #define G5_STORE(s)                                                                 \
;   {                                                                                 \
;     _Pragma("unroll") for (int i_ = 0; i_ < 4; ++i_) *(u32x4*)(Sw + (s) * STG + i_ * 64 * GS) = ra[i_]; \
;     _Pragma("unroll") for (int i_ = 0; i_ < 4; ++i_) *(u32x4*)(Sw + (s) * STG + 256 * GS + i_ * 64 * GS) = rb[i_]; \
;   }
; template <typename Epi>
; DI void gemm_tile512(const u16* __restrict__ A, int lda, const u16* __restrict__ Bt, int ldb, int K, char* lds_all, Epi epi) {
;     ...
;   for (int kt = 0; kt + 2 < nk; ++kt) {
;     const int cur = kt & 1;
;     G5_COMPUTE(cur);
;     G5_STORE(cur ^ 1);
;     G5_LOAD((kt + 2) << 6);
;     __syncthreads();
;   }
	ds_read_b128 v[194:197], v179 offset:36864
	ds_read_b128 v[166:169], v178
	v_mfma_f32_32x32x16_bf16 v[114:129], v[218:221], v[234:237], v[114:129]
	ds_read_b128 v[198:201], v179 offset:41472
	v_mfma_f32_32x32x16_bf16 v[98:113], v[218:221], v[202:205], v[98:113]
	ds_read_b128 v[170:173], v178 offset:4608
	v_mfma_f32_32x32x16_bf16 v[82:97], v[222:225], v[234:237], v[82:97]
	ds_read_b128 v[174:177], v178 offset:9216
	v_mfma_f32_32x32x16_bf16 v[66:81], v[222:225], v[202:205], v[66:81]
	ds_read_b128 v[190:193], v178 offset:13824
	v_mfma_f32_32x32x16_bf16 v[50:65], v[226:229], v[234:237], v[50:65]
	v_mfma_f32_32x32x16_bf16 v[34:49], v[226:229], v[202:205], v[34:49]
	v_mfma_f32_32x32x16_bf16 v[18:33], v[230:233], v[234:237], v[18:33]
	v_mfma_f32_32x32x16_bf16 v[2:17], v[230:233], v[202:205], v[2:17]
	s_waitcnt lgkmcnt(4)
	v_mfma_f32_32x32x16_bf16 v[114:129], v[166:169], v[194:197], v[114:129]
	ds_read_b128 v[234:237], v179 offset:36896
	s_waitcnt lgkmcnt(4)
	v_mfma_f32_32x32x16_bf16 v[98:113], v[166:169], v[198:201], v[98:113]
	ds_read_b128 v[218:221], v178 offset:32
	s_waitcnt vmcnt(15)
	ds_write_b128 v180, v[182:185]
	global_load_dwordx4 v[182:185], v206, s[98:99]
	s_waitcnt lgkmcnt(5)
	v_mfma_f32_32x32x16_bf16 v[82:97], v[170:173], v[194:197], v[82:97]
	ds_read_b128 v[202:205], v179 offset:41504
	v_mfma_f32_32x32x16_bf16 v[66:81], v[170:173], v[198:201], v[66:81]
	ds_read_b128 v[222:225], v178 offset:4640
	s_waitcnt vmcnt(15)
	ds_write_b128 v180, v[186:189] offset:9216
	global_load_dwordx4 v[186:189], v207, s[98:99]
	s_waitcnt lgkmcnt(7)
	v_mfma_f32_32x32x16_bf16 v[50:65], v[174:177], v[194:197], v[50:65]
	ds_read_b128 v[226:229], v178 offset:9248
	v_mfma_f32_32x32x16_bf16 v[34:49], v[174:177], v[198:201], v[34:49]
	ds_read_b128 v[230:233], v178 offset:13856
	s_waitcnt vmcnt(15)
	ds_write_b128 v180, v[210:213] offset:18432
	global_load_dwordx4 v[210:213], v208, s[98:99]
	s_waitcnt lgkmcnt(9)
	v_mfma_f32_32x32x16_bf16 v[18:33], v[190:193], v[194:197], v[18:33]
	v_mfma_f32_32x32x16_bf16 v[2:17], v[190:193], v[198:201], v[2:17]
	s_waitcnt vmcnt(15)
	ds_write_b128 v180, v[240:243] offset:27648
	global_load_dwordx4 v[240:243], v238, s[98:99]
	s_waitcnt lgkmcnt(8)
	v_mfma_f32_32x32x16_bf16 v[114:129], v[218:221], v[234:237], v[114:129]
	ds_read_b128 v[194:197], v179 offset:36928
	s_waitcnt lgkmcnt(7)
	v_mfma_f32_32x32x16_bf16 v[98:113], v[218:221], v[202:205], v[98:113]
	ds_read_b128 v[166:169], v178 offset:64
	s_waitcnt vmcnt(7)
	ds_write_b128 v180, v[146:149] offset:36864
	global_load_dwordx4 v[146:149], v206, s[100:101]
	s_waitcnt lgkmcnt(8)
	v_mfma_f32_32x32x16_bf16 v[82:97], v[222:225], v[234:237], v[82:97]
	ds_read_b128 v[198:201], v179 offset:41536
	v_mfma_f32_32x32x16_bf16 v[66:81], v[222:225], v[202:205], v[66:81]
	ds_read_b128 v[170:173], v178 offset:4672
	s_waitcnt vmcnt(7)
	ds_write_b128 v180, v[150:153] offset:46080
	global_load_dwordx4 v[150:153], v207, s[100:101]
	s_waitcnt lgkmcnt(9)
	v_mfma_f32_32x32x16_bf16 v[50:65], v[226:229], v[234:237], v[50:65]
	ds_read_b128 v[174:177], v178 offset:9280
	v_mfma_f32_32x32x16_bf16 v[34:49], v[226:229], v[202:205], v[34:49]
	ds_read_b128 v[190:193], v178 offset:13888
	s_waitcnt vmcnt(7)
	ds_write_b128 v180, v[154:157] offset:55296
	global_load_dwordx4 v[154:157], v208, s[100:101]
	s_waitcnt lgkmcnt(11)
	v_mfma_f32_32x32x16_bf16 v[18:33], v[230:233], v[234:237], v[18:33]
	v_mfma_f32_32x32x16_bf16 v[2:17], v[230:233], v[202:205], v[2:17]
	s_waitcnt vmcnt(7)
	ds_write_b128 v180, v[158:161] offset:64512
	global_load_dwordx4 v[158:161], v238, s[100:101]
	v_subrev_u32_e32 v180, s14, v180
	s_waitcnt lgkmcnt(8)
	v_mfma_f32_32x32x16_bf16 v[114:129], v[166:169], v[194:197], v[114:129]
	ds_read_b128 v[234:237], v179 offset:36960
	s_waitcnt lgkmcnt(7)
	v_mfma_f32_32x32x16_bf16 v[98:113], v[166:169], v[198:201], v[98:113]
	ds_read_b128 v[218:221], v178 offset:96
	s_waitcnt lgkmcnt(7)
	v_mfma_f32_32x32x16_bf16 v[82:97], v[170:173], v[194:197], v[82:97]
	ds_read_b128 v[202:205], v179 offset:41568
	v_mfma_f32_32x32x16_bf16 v[66:81], v[170:173], v[198:201], v[66:81]
	ds_read_b128 v[222:225], v178 offset:4704
	s_waitcnt lgkmcnt(7)
	v_mfma_f32_32x32x16_bf16 v[50:65], v[174:177], v[194:197], v[50:65]
	ds_read_b128 v[226:229], v178 offset:9312
	v_mfma_f32_32x32x16_bf16 v[34:49], v[174:177], v[198:201], v[34:49]
	ds_read_b128 v[230:233], v178 offset:13920
	v_add_u32_e32 v178, s14, v178
	v_add_u32_e32 v179, s14, v179
	s_waitcnt lgkmcnt(8)
	v_mfma_f32_32x32x16_bf16 v[18:33], v[190:193], v[194:197], v[18:33]
	v_mfma_f32_32x32x16_bf16 v[2:17], v[190:193], v[198:201], v[2:17]
	s_sub_u32 s14, 0, s14
	s_add_u32 s98, s98, 0x80
	s_addc_u32 s99, s99, 0
	s_add_u32 s100, s100, 0x80
	s_addc_u32 s101, s101, 0
	s_waitcnt lgkmcnt(0)
	s_sub_u32 s15, s15, 1
	s_cmp_lg_u32 s15, 0
	s_cbranch_scc1 .Lgemm2_loop_m3
	s_barrier
; #define G5_LOAD(k0)                                                                 \
;   {                                                                                 \
;     _Pragma("unroll") for (int i_ = 0; i_ < 4; ++i_) ra[i_] = ldg16(Ap + (size_t)(i_ * 64) * lda + (k0)); \
;     _Pragma("unroll") for (int i_ = 0; i_ < 4; ++i_) rb[i_] = ldg16(Bp + (size_t)(i_ * 64) * ldb + (k0)); \
;   }
; #define G5_STORE(s)                                                                 \
;   {                                                                                 \
;     _Pragma("unroll") for (int i_ = 0; i_ < 4; ++i_) *(u32x4*)(Sw + (s) * STG + i_ * 64 * GS) = ra[i_]; \
;     _Pragma("unroll") for (int i_ = 0; i_ < 4; ++i_) *(u32x4*)(Sw + (s) * STG + 256 * GS + i_ * 64 * GS) = rb[i_]; \
;   }
; template <typename Epi>
; DI void gemm_tile512(const u16* __restrict__ A, int lda, const u16* __restrict__ Bt, int ldb, int K, char* lds_all, Epi epi) {
;     ...
;   for (int kt = 0; kt + 2 < nk; ++kt) {
;     const int cur = kt & 1;
;     G5_COMPUTE(cur);
;     G5_STORE(cur ^ 1);
;     G5_LOAD((kt + 2) << 6);
;     __syncthreads();
;   }
;   {
;     const int cur = (nk - 2) & 1;
;     G5_COMPUTE(cur);
;     G5_STORE(cur ^ 1);
;     __syncthreads();
	ds_read_b128 v[194:197], v179 offset:36864
	ds_read_b128 v[166:169], v178
	v_mfma_f32_32x32x16_bf16 v[114:129], v[218:221], v[234:237], v[114:129]
	ds_read_b128 v[198:201], v179 offset:41472
	v_mfma_f32_32x32x16_bf16 v[98:113], v[218:221], v[202:205], v[98:113]
	ds_read_b128 v[170:173], v178 offset:4608
	v_mfma_f32_32x32x16_bf16 v[82:97], v[222:225], v[234:237], v[82:97]
	ds_read_b128 v[174:177], v178 offset:9216
	v_mfma_f32_32x32x16_bf16 v[66:81], v[222:225], v[202:205], v[66:81]
	ds_read_b128 v[190:193], v178 offset:13824
	v_mfma_f32_32x32x16_bf16 v[50:65], v[226:229], v[234:237], v[50:65]
	v_mfma_f32_32x32x16_bf16 v[34:49], v[226:229], v[202:205], v[34:49]
	v_mfma_f32_32x32x16_bf16 v[18:33], v[230:233], v[234:237], v[18:33]
	v_mfma_f32_32x32x16_bf16 v[2:17], v[230:233], v[202:205], v[2:17]
	s_waitcnt lgkmcnt(4)
	v_mfma_f32_32x32x16_bf16 v[114:129], v[166:169], v[194:197], v[114:129]
	ds_read_b128 v[234:237], v179 offset:36896
	s_waitcnt lgkmcnt(4)
	v_mfma_f32_32x32x16_bf16 v[98:113], v[166:169], v[198:201], v[98:113]
	ds_read_b128 v[218:221], v178 offset:32
	s_waitcnt vmcnt(15)
	ds_write_b128 v180, v[130:133]
	global_load_dwordx4 v[130:133], v206, s[98:99]
	s_waitcnt lgkmcnt(5)
	v_mfma_f32_32x32x16_bf16 v[82:97], v[170:173], v[194:197], v[82:97]
	ds_read_b128 v[202:205], v179 offset:41504
	v_mfma_f32_32x32x16_bf16 v[66:81], v[170:173], v[198:201], v[66:81]
	ds_read_b128 v[222:225], v178 offset:4640
	s_waitcnt vmcnt(15)
	ds_write_b128 v180, v[134:137] offset:9216
	global_load_dwordx4 v[134:137], v207, s[98:99]
	s_waitcnt lgkmcnt(7)
	v_mfma_f32_32x32x16_bf16 v[50:65], v[174:177], v[194:197], v[50:65]
	ds_read_b128 v[226:229], v178 offset:9248
	v_mfma_f32_32x32x16_bf16 v[34:49], v[174:177], v[198:201], v[34:49]
	ds_read_b128 v[230:233], v178 offset:13856
	s_waitcnt vmcnt(15)
	ds_write_b128 v180, v[138:141] offset:18432
	global_load_dwordx4 v[138:141], v208, s[98:99]
	s_waitcnt lgkmcnt(9)
	v_mfma_f32_32x32x16_bf16 v[18:33], v[190:193], v[194:197], v[18:33]
	v_mfma_f32_32x32x16_bf16 v[2:17], v[190:193], v[198:201], v[2:17]
	s_waitcnt vmcnt(15)
	ds_write_b128 v180, v[142:145] offset:27648
	global_load_dwordx4 v[142:145], v238, s[98:99]
	s_waitcnt lgkmcnt(8)
	v_mfma_f32_32x32x16_bf16 v[114:129], v[218:221], v[234:237], v[114:129]
	ds_read_b128 v[194:197], v179 offset:36928
	s_waitcnt lgkmcnt(7)
	v_mfma_f32_32x32x16_bf16 v[98:113], v[218:221], v[202:205], v[98:113]
	ds_read_b128 v[166:169], v178 offset:64
	s_waitcnt vmcnt(7)
	ds_write_b128 v180, v[146:149] offset:36864
	global_load_dwordx4 v[146:149], v206, s[100:101]
	s_waitcnt lgkmcnt(8)
	v_mfma_f32_32x32x16_bf16 v[82:97], v[222:225], v[234:237], v[82:97]
	ds_read_b128 v[198:201], v179 offset:41536
	v_mfma_f32_32x32x16_bf16 v[66:81], v[222:225], v[202:205], v[66:81]
	ds_read_b128 v[170:173], v178 offset:4672
	s_waitcnt vmcnt(7)
	ds_write_b128 v180, v[150:153] offset:46080
	global_load_dwordx4 v[150:153], v207, s[100:101]
	s_waitcnt lgkmcnt(9)
	v_mfma_f32_32x32x16_bf16 v[50:65], v[226:229], v[234:237], v[50:65]
	ds_read_b128 v[174:177], v178 offset:9280
	v_mfma_f32_32x32x16_bf16 v[34:49], v[226:229], v[202:205], v[34:49]
	ds_read_b128 v[190:193], v178 offset:13888
	s_waitcnt vmcnt(7)
	ds_write_b128 v180, v[154:157] offset:55296
	global_load_dwordx4 v[154:157], v208, s[100:101]
	s_waitcnt lgkmcnt(11)
	v_mfma_f32_32x32x16_bf16 v[18:33], v[230:233], v[234:237], v[18:33]
	v_mfma_f32_32x32x16_bf16 v[2:17], v[230:233], v[202:205], v[2:17]
	s_waitcnt vmcnt(7)
	ds_write_b128 v180, v[158:161] offset:64512
	global_load_dwordx4 v[158:161], v238, s[100:101]
	v_subrev_u32_e32 v180, s14, v180
	s_waitcnt lgkmcnt(8)
	v_mfma_f32_32x32x16_bf16 v[114:129], v[166:169], v[194:197], v[114:129]
	ds_read_b128 v[234:237], v179 offset:36960
	s_waitcnt lgkmcnt(7)
	v_mfma_f32_32x32x16_bf16 v[98:113], v[166:169], v[198:201], v[98:113]
	ds_read_b128 v[218:221], v178 offset:96
	s_waitcnt lgkmcnt(7)
	v_mfma_f32_32x32x16_bf16 v[82:97], v[170:173], v[194:197], v[82:97]
	ds_read_b128 v[202:205], v179 offset:41568
	v_mfma_f32_32x32x16_bf16 v[66:81], v[170:173], v[198:201], v[66:81]
	ds_read_b128 v[222:225], v178 offset:4704
	s_waitcnt lgkmcnt(7)
	v_mfma_f32_32x32x16_bf16 v[50:65], v[174:177], v[194:197], v[50:65]
	ds_read_b128 v[226:229], v178 offset:9312
	v_mfma_f32_32x32x16_bf16 v[34:49], v[174:177], v[198:201], v[34:49]
	ds_read_b128 v[230:233], v178 offset:13920
	v_add_u32_e32 v178, s14, v178
	v_add_u32_e32 v179, s14, v179
	s_waitcnt lgkmcnt(8)
	v_mfma_f32_32x32x16_bf16 v[18:33], v[190:193], v[194:197], v[18:33]
	v_mfma_f32_32x32x16_bf16 v[2:17], v[190:193], v[198:201], v[2:17]
	s_sub_u32 s14, 0, s14
	s_add_u32 s98, s98, 0x80
	s_addc_u32 s99, s99, 0
	s_add_u32 s100, s100, 0x80
	s_addc_u32 s101, s101, 0
	s_waitcnt lgkmcnt(0)
	s_barrier
; #define G5_LOAD(k0)                                                                 \
;   {                                                                                 \
;     _Pragma("unroll") for (int i_ = 0; i_ < 4; ++i_) ra[i_] = ldg16(Ap + (size_t)(i_ * 64) * lda + (k0)); \
;     _Pragma("unroll") for (int i_ = 0; i_ < 4; ++i_) rb[i_] = ldg16(Bp + (size_t)(i_ * 64) * ldb + (k0)); \
;   }
; #define G5_STORE(s)                                                                 \
;   {                                                                                 \
;     _Pragma("unroll") for (int i_ = 0; i_ < 4; ++i_) *(u32x4*)(Sw + (s) * STG + i_ * 64 * GS) = ra[i_]; \
;     _Pragma("unroll") for (int i_ = 0; i_ < 4; ++i_) *(u32x4*)(Sw + (s) * STG + 256 * GS + i_ * 64 * GS) = rb[i_]; \
;   }
; template <typename Epi>
; DI void gemm_tile512(const u16* __restrict__ A, int lda, const u16* __restrict__ Bt, int ldb, int K, char* lds_all, Epi epi) {
;     ...
;   for (int kt = 0; kt + 2 < nk; ++kt) {
;     const int cur = kt & 1;
;     G5_COMPUTE(cur);
;     G5_STORE(cur ^ 1);
;     G5_LOAD((kt + 2) << 6);
;     __syncthreads();
;   }
;   {
;     const int cur = (nk - 2) & 1;
;     G5_COMPUTE(cur);
;     G5_STORE(cur ^ 1);
;     __syncthreads();
	ds_read_b128 v[194:197], v179 offset:36864
	ds_read_b128 v[166:169], v178
	v_mfma_f32_32x32x16_bf16 v[114:129], v[218:221], v[234:237], v[114:129]
	ds_read_b128 v[198:201], v179 offset:41472
	v_mfma_f32_32x32x16_bf16 v[98:113], v[218:221], v[202:205], v[98:113]
	ds_read_b128 v[170:173], v178 offset:4608
	v_mfma_f32_32x32x16_bf16 v[82:97], v[222:225], v[234:237], v[82:97]
	ds_read_b128 v[174:177], v178 offset:9216
	v_mfma_f32_32x32x16_bf16 v[66:81], v[222:225], v[202:205], v[66:81]
	ds_read_b128 v[190:193], v178 offset:13824
	v_mfma_f32_32x32x16_bf16 v[50:65], v[226:229], v[234:237], v[50:65]
	v_mfma_f32_32x32x16_bf16 v[34:49], v[226:229], v[202:205], v[34:49]
	v_mfma_f32_32x32x16_bf16 v[18:33], v[230:233], v[234:237], v[18:33]
	v_mfma_f32_32x32x16_bf16 v[2:17], v[230:233], v[202:205], v[2:17]
	s_waitcnt lgkmcnt(4)
	v_mfma_f32_32x32x16_bf16 v[114:129], v[166:169], v[194:197], v[114:129]
	ds_read_b128 v[234:237], v179 offset:36896
	s_waitcnt lgkmcnt(4)
	v_mfma_f32_32x32x16_bf16 v[98:113], v[166:169], v[198:201], v[98:113]
	ds_read_b128 v[218:221], v178 offset:32
	s_waitcnt vmcnt(15)
	ds_write_b128 v180, v[182:185]
	s_waitcnt lgkmcnt(5)
	v_mfma_f32_32x32x16_bf16 v[82:97], v[170:173], v[194:197], v[82:97]
	ds_read_b128 v[202:205], v179 offset:41504
	v_mfma_f32_32x32x16_bf16 v[66:81], v[170:173], v[198:201], v[66:81]
	ds_read_b128 v[222:225], v178 offset:4640
	s_waitcnt vmcnt(14)
	ds_write_b128 v180, v[186:189] offset:9216
	s_waitcnt lgkmcnt(7)
	v_mfma_f32_32x32x16_bf16 v[50:65], v[174:177], v[194:197], v[50:65]
	ds_read_b128 v[226:229], v178 offset:9248
	v_mfma_f32_32x32x16_bf16 v[34:49], v[174:177], v[198:201], v[34:49]
	ds_read_b128 v[230:233], v178 offset:13856
	s_waitcnt vmcnt(13)
	ds_write_b128 v180, v[210:213] offset:18432
	s_waitcnt lgkmcnt(9)
	v_mfma_f32_32x32x16_bf16 v[18:33], v[190:193], v[194:197], v[18:33]
	v_mfma_f32_32x32x16_bf16 v[2:17], v[190:193], v[198:201], v[2:17]
	s_waitcnt vmcnt(12)
	ds_write_b128 v180, v[240:243] offset:27648
	s_waitcnt lgkmcnt(8)
	v_mfma_f32_32x32x16_bf16 v[114:129], v[218:221], v[234:237], v[114:129]
	ds_read_b128 v[194:197], v179 offset:36928
	s_waitcnt lgkmcnt(7)
	v_mfma_f32_32x32x16_bf16 v[98:113], v[218:221], v[202:205], v[98:113]
	ds_read_b128 v[166:169], v178 offset:64
	s_waitcnt vmcnt(3)
	ds_write_b128 v180, v[146:149] offset:36864
	global_load_dwordx4 v[146:149], v206, s[100:101]
	s_waitcnt lgkmcnt(8)
	v_mfma_f32_32x32x16_bf16 v[82:97], v[222:225], v[234:237], v[82:97]
	ds_read_b128 v[198:201], v179 offset:41536
	v_mfma_f32_32x32x16_bf16 v[66:81], v[222:225], v[202:205], v[66:81]
	ds_read_b128 v[170:173], v178 offset:4672
	s_waitcnt vmcnt(3)
	ds_write_b128 v180, v[150:153] offset:46080
	global_load_dwordx4 v[150:153], v207, s[100:101]
	s_waitcnt lgkmcnt(9)
	v_mfma_f32_32x32x16_bf16 v[50:65], v[226:229], v[234:237], v[50:65]
	ds_read_b128 v[174:177], v178 offset:9280
	v_mfma_f32_32x32x16_bf16 v[34:49], v[226:229], v[202:205], v[34:49]
	ds_read_b128 v[190:193], v178 offset:13888
	s_waitcnt vmcnt(3)
	ds_write_b128 v180, v[154:157] offset:55296
	global_load_dwordx4 v[154:157], v208, s[100:101]
	s_waitcnt lgkmcnt(11)
	v_mfma_f32_32x32x16_bf16 v[18:33], v[230:233], v[234:237], v[18:33]
	v_mfma_f32_32x32x16_bf16 v[2:17], v[230:233], v[202:205], v[2:17]
	s_waitcnt vmcnt(3)
	ds_write_b128 v180, v[158:161] offset:64512
	global_load_dwordx4 v[158:161], v238, s[100:101]
	v_subrev_u32_e32 v180, s14, v180
	s_waitcnt lgkmcnt(8)
	v_mfma_f32_32x32x16_bf16 v[114:129], v[166:169], v[194:197], v[114:129]
	ds_read_b128 v[234:237], v179 offset:36960
	s_waitcnt lgkmcnt(7)
	v_mfma_f32_32x32x16_bf16 v[98:113], v[166:169], v[198:201], v[98:113]
	ds_read_b128 v[218:221], v178 offset:96
	s_waitcnt lgkmcnt(7)
	v_mfma_f32_32x32x16_bf16 v[82:97], v[170:173], v[194:197], v[82:97]
	ds_read_b128 v[202:205], v179 offset:41568
	v_mfma_f32_32x32x16_bf16 v[66:81], v[170:173], v[198:201], v[66:81]
	ds_read_b128 v[222:225], v178 offset:4704
	s_waitcnt lgkmcnt(7)
	v_mfma_f32_32x32x16_bf16 v[50:65], v[174:177], v[194:197], v[50:65]
	ds_read_b128 v[226:229], v178 offset:9312
	v_mfma_f32_32x32x16_bf16 v[34:49], v[174:177], v[198:201], v[34:49]
	ds_read_b128 v[230:233], v178 offset:13920
	v_add_u32_e32 v178, s14, v178
	v_add_u32_e32 v179, s14, v179
	s_waitcnt lgkmcnt(8)
	v_mfma_f32_32x32x16_bf16 v[18:33], v[190:193], v[194:197], v[18:33]
	v_mfma_f32_32x32x16_bf16 v[2:17], v[190:193], v[198:201], v[2:17]
	s_sub_u32 s14, 0, s14
	s_add_u32 s98, s98, 0x80
	s_addc_u32 s99, s99, 0
	s_add_u32 s100, s100, 0x80
	s_addc_u32 s101, s101, 0
	s_waitcnt lgkmcnt(0)
	s_barrier
; #define G5_STORE(s)                                                                 \
;   {                                                                                 \
;     _Pragma("unroll") for (int i_ = 0; i_ < 4; ++i_) *(u32x4*)(Sw + (s) * STG + i_ * 64 * GS) = ra[i_]; \
;     _Pragma("unroll") for (int i_ = 0; i_ < 4; ++i_) *(u32x4*)(Sw + (s) * STG + 256 * GS + i_ * 64 * GS) = rb[i_]; \
;   }
; template <typename Epi>
; DI void gemm_tile512(const u16* __restrict__ A, int lda, const u16* __restrict__ Bt, int ldb, int K, char* lds_all, Epi epi) {
;     ...
;   {
;     const int cur = (nk - 2) & 1;
;     G5_COMPUTE(cur);
;     G5_STORE(cur ^ 1);
;     __syncthreads();
	ds_read_b128 v[194:197], v179 offset:36864
	ds_read_b128 v[166:169], v178
	v_mfma_f32_32x32x16_bf16 v[114:129], v[218:221], v[234:237], v[114:129]
	ds_read_b128 v[198:201], v179 offset:41472
	v_mfma_f32_32x32x16_bf16 v[98:113], v[218:221], v[202:205], v[98:113]
	ds_read_b128 v[170:173], v178 offset:4608
	v_mfma_f32_32x32x16_bf16 v[82:97], v[222:225], v[234:237], v[82:97]
	ds_read_b128 v[174:177], v178 offset:9216
	v_mfma_f32_32x32x16_bf16 v[66:81], v[222:225], v[202:205], v[66:81]
	ds_read_b128 v[190:193], v178 offset:13824
	v_mfma_f32_32x32x16_bf16 v[50:65], v[226:229], v[234:237], v[50:65]
	v_mfma_f32_32x32x16_bf16 v[34:49], v[226:229], v[202:205], v[34:49]
	v_mfma_f32_32x32x16_bf16 v[18:33], v[230:233], v[234:237], v[18:33]
	v_mfma_f32_32x32x16_bf16 v[2:17], v[230:233], v[202:205], v[2:17]
	s_waitcnt lgkmcnt(4)
	v_mfma_f32_32x32x16_bf16 v[114:129], v[166:169], v[194:197], v[114:129]
	ds_read_b128 v[234:237], v179 offset:36896
	s_waitcnt lgkmcnt(4)
	v_mfma_f32_32x32x16_bf16 v[98:113], v[166:169], v[198:201], v[98:113]
	ds_read_b128 v[218:221], v178 offset:32
	s_waitcnt vmcnt(11)
	ds_write_b128 v180, v[130:133]
	s_waitcnt lgkmcnt(5)
	v_mfma_f32_32x32x16_bf16 v[82:97], v[170:173], v[194:197], v[82:97]
	ds_read_b128 v[202:205], v179 offset:41504
	v_mfma_f32_32x32x16_bf16 v[66:81], v[170:173], v[198:201], v[66:81]
	ds_read_b128 v[222:225], v178 offset:4640
	s_waitcnt vmcnt(10)
	ds_write_b128 v180, v[134:137] offset:9216
	s_waitcnt lgkmcnt(7)
	v_mfma_f32_32x32x16_bf16 v[50:65], v[174:177], v[194:197], v[50:65]
	ds_read_b128 v[226:229], v178 offset:9248
	v_mfma_f32_32x32x16_bf16 v[34:49], v[174:177], v[198:201], v[34:49]
	ds_read_b128 v[230:233], v178 offset:13856
	s_waitcnt vmcnt(9)
	ds_write_b128 v180, v[138:141] offset:18432
	s_waitcnt lgkmcnt(9)
	v_mfma_f32_32x32x16_bf16 v[18:33], v[190:193], v[194:197], v[18:33]
	v_mfma_f32_32x32x16_bf16 v[2:17], v[190:193], v[198:201], v[2:17]
	s_waitcnt vmcnt(8)
	ds_write_b128 v180, v[142:145] offset:27648
	s_waitcnt lgkmcnt(8)
	v_mfma_f32_32x32x16_bf16 v[114:129], v[218:221], v[234:237], v[114:129]
	ds_read_b128 v[194:197], v179 offset:36928
	s_waitcnt lgkmcnt(7)
	v_mfma_f32_32x32x16_bf16 v[98:113], v[218:221], v[202:205], v[98:113]
	ds_read_b128 v[166:169], v178 offset:64
	s_waitcnt vmcnt(3)
	ds_write_b128 v180, v[146:149] offset:36864
	s_waitcnt lgkmcnt(8)
	v_mfma_f32_32x32x16_bf16 v[82:97], v[222:225], v[234:237], v[82:97]
	ds_read_b128 v[198:201], v179 offset:41536
	v_mfma_f32_32x32x16_bf16 v[66:81], v[222:225], v[202:205], v[66:81]
	ds_read_b128 v[170:173], v178 offset:4672
	s_waitcnt vmcnt(2)
	ds_write_b128 v180, v[150:153] offset:46080
	s_waitcnt lgkmcnt(9)
	v_mfma_f32_32x32x16_bf16 v[50:65], v[226:229], v[234:237], v[50:65]
	ds_read_b128 v[174:177], v178 offset:9280
	v_mfma_f32_32x32x16_bf16 v[34:49], v[226:229], v[202:205], v[34:49]
	ds_read_b128 v[190:193], v178 offset:13888
	s_waitcnt vmcnt(1)
	ds_write_b128 v180, v[154:157] offset:55296
	s_waitcnt lgkmcnt(11)
	v_mfma_f32_32x32x16_bf16 v[18:33], v[230:233], v[234:237], v[18:33]
	v_mfma_f32_32x32x16_bf16 v[2:17], v[230:233], v[202:205], v[2:17]
	s_waitcnt vmcnt(0)
	ds_write_b128 v180, v[158:161] offset:64512
	v_subrev_u32_e32 v180, s14, v180
	s_waitcnt lgkmcnt(8)
	v_mfma_f32_32x32x16_bf16 v[114:129], v[166:169], v[194:197], v[114:129]
	ds_read_b128 v[234:237], v179 offset:36960
	s_waitcnt lgkmcnt(7)
	v_mfma_f32_32x32x16_bf16 v[98:113], v[166:169], v[198:201], v[98:113]
	ds_read_b128 v[218:221], v178 offset:96
	s_waitcnt lgkmcnt(7)
	v_mfma_f32_32x32x16_bf16 v[82:97], v[170:173], v[194:197], v[82:97]
	ds_read_b128 v[202:205], v179 offset:41568
	v_mfma_f32_32x32x16_bf16 v[66:81], v[170:173], v[198:201], v[66:81]
	ds_read_b128 v[222:225], v178 offset:4704
	s_waitcnt lgkmcnt(7)
	v_mfma_f32_32x32x16_bf16 v[50:65], v[174:177], v[194:197], v[50:65]
	ds_read_b128 v[226:229], v178 offset:9312
	v_mfma_f32_32x32x16_bf16 v[34:49], v[174:177], v[198:201], v[34:49]
	ds_read_b128 v[230:233], v178 offset:13920
	v_add_u32_e32 v178, s14, v178
	v_add_u32_e32 v179, s14, v179
	s_waitcnt lgkmcnt(8)
	v_mfma_f32_32x32x16_bf16 v[18:33], v[190:193], v[194:197], v[18:33]
	v_mfma_f32_32x32x16_bf16 v[2:17], v[190:193], v[198:201], v[2:17]
	s_sub_u32 s14, 0, s14
	s_add_u32 s98, s98, 0x80
	s_addc_u32 s99, s99, 0
	s_add_u32 s100, s100, 0x80
	s_addc_u32 s101, s101, 0
	s_waitcnt lgkmcnt(0)
	s_barrier
; #define G5_STORE(s)                                                                 \
;   {                                                                                 \
;     _Pragma("unroll") for (int i_ = 0; i_ < 4; ++i_) *(u32x4*)(Sw + (s) * STG + i_ * 64 * GS) = ra[i_]; \
;     _Pragma("unroll") for (int i_ = 0; i_ < 4; ++i_) *(u32x4*)(Sw + (s) * STG + 256 * GS + i_ * 64 * GS) = rb[i_]; \
;   }
; template <typename Epi>
; DI void gemm_tile512(const u16* __restrict__ A, int lda, const u16* __restrict__ Bt, int ldb, int K, char* lds_all, Epi epi) {
;     ...
;   {
;     const int cur = (nk - 2) & 1;
;     G5_COMPUTE(cur);
;     G5_STORE(cur ^ 1);
;     __syncthreads();
;     G5_COMPUTE(cur ^ 1);
;   }
	ds_read_b128 v[194:197], v179 offset:36864
	ds_read_b128 v[166:169], v178
	v_mfma_f32_32x32x16_bf16 v[114:129], v[218:221], v[234:237], v[114:129]
	ds_read_b128 v[198:201], v179 offset:41472
	v_mfma_f32_32x32x16_bf16 v[98:113], v[218:221], v[202:205], v[98:113]
	ds_read_b128 v[170:173], v178 offset:4608
	v_mfma_f32_32x32x16_bf16 v[82:97], v[222:225], v[234:237], v[82:97]
	ds_read_b128 v[174:177], v178 offset:9216
	v_mfma_f32_32x32x16_bf16 v[66:81], v[222:225], v[202:205], v[66:81]
	ds_read_b128 v[190:193], v178 offset:13824
	v_mfma_f32_32x32x16_bf16 v[50:65], v[226:229], v[234:237], v[50:65]
	v_mfma_f32_32x32x16_bf16 v[34:49], v[226:229], v[202:205], v[34:49]
	v_mfma_f32_32x32x16_bf16 v[18:33], v[230:233], v[234:237], v[18:33]
	v_mfma_f32_32x32x16_bf16 v[2:17], v[230:233], v[202:205], v[2:17]
	s_waitcnt lgkmcnt(4)
	v_mfma_f32_32x32x16_bf16 v[114:129], v[166:169], v[194:197], v[114:129]
	ds_read_b128 v[234:237], v179 offset:36896
	s_waitcnt lgkmcnt(4)
	v_mfma_f32_32x32x16_bf16 v[98:113], v[166:169], v[198:201], v[98:113]
	ds_read_b128 v[218:221], v178 offset:32
	s_waitcnt lgkmcnt(4)
	v_mfma_f32_32x32x16_bf16 v[82:97], v[170:173], v[194:197], v[82:97]
	ds_read_b128 v[202:205], v179 offset:41504
	v_mfma_f32_32x32x16_bf16 v[66:81], v[170:173], v[198:201], v[66:81]
	ds_read_b128 v[222:225], v178 offset:4640
	s_waitcnt lgkmcnt(5)
	v_mfma_f32_32x32x16_bf16 v[50:65], v[174:177], v[194:197], v[50:65]
	ds_read_b128 v[226:229], v178 offset:9248
	v_mfma_f32_32x32x16_bf16 v[34:49], v[174:177], v[198:201], v[34:49]
	ds_read_b128 v[230:233], v178 offset:13856
	s_waitcnt lgkmcnt(6)
	v_mfma_f32_32x32x16_bf16 v[18:33], v[190:193], v[194:197], v[18:33]
	v_mfma_f32_32x32x16_bf16 v[2:17], v[190:193], v[198:201], v[2:17]
	s_waitcnt lgkmcnt(4)
	v_mfma_f32_32x32x16_bf16 v[114:129], v[218:221], v[234:237], v[114:129]
	ds_read_b128 v[194:197], v179 offset:36928
	s_waitcnt lgkmcnt(4)
	v_mfma_f32_32x32x16_bf16 v[98:113], v[218:221], v[202:205], v[98:113]
	ds_read_b128 v[166:169], v178 offset:64
	s_waitcnt lgkmcnt(4)
	v_mfma_f32_32x32x16_bf16 v[82:97], v[222:225], v[234:237], v[82:97]
	ds_read_b128 v[198:201], v179 offset:41536
	v_mfma_f32_32x32x16_bf16 v[66:81], v[222:225], v[202:205], v[66:81]
	ds_read_b128 v[170:173], v178 offset:4672
	s_waitcnt lgkmcnt(5)
	v_mfma_f32_32x32x16_bf16 v[50:65], v[226:229], v[234:237], v[50:65]
	ds_read_b128 v[174:177], v178 offset:9280
	v_mfma_f32_32x32x16_bf16 v[34:49], v[226:229], v[202:205], v[34:49]
	ds_read_b128 v[190:193], v178 offset:13888
	s_waitcnt lgkmcnt(6)
	v_mfma_f32_32x32x16_bf16 v[18:33], v[230:233], v[234:237], v[18:33]
	v_mfma_f32_32x32x16_bf16 v[2:17], v[230:233], v[202:205], v[2:17]
	s_waitcnt lgkmcnt(4)
	v_mfma_f32_32x32x16_bf16 v[114:129], v[166:169], v[194:197], v[114:129]
	ds_read_b128 v[234:237], v179 offset:36960
	s_waitcnt lgkmcnt(4)
	v_mfma_f32_32x32x16_bf16 v[98:113], v[166:169], v[198:201], v[98:113]
	ds_read_b128 v[218:221], v178 offset:96
	s_waitcnt lgkmcnt(4)
	v_mfma_f32_32x32x16_bf16 v[82:97], v[170:173], v[194:197], v[82:97]
	ds_read_b128 v[202:205], v179 offset:41568
	v_mfma_f32_32x32x16_bf16 v[66:81], v[170:173], v[198:201], v[66:81]
	ds_read_b128 v[222:225], v178 offset:4704
	s_waitcnt lgkmcnt(5)
	v_mfma_f32_32x32x16_bf16 v[50:65], v[174:177], v[194:197], v[50:65]
	ds_read_b128 v[226:229], v178 offset:9312
	v_mfma_f32_32x32x16_bf16 v[34:49], v[174:177], v[198:201], v[34:49]
	ds_read_b128 v[230:233], v178 offset:13920
	s_waitcnt lgkmcnt(6)
	v_mfma_f32_32x32x16_bf16 v[18:33], v[190:193], v[194:197], v[18:33]
	v_mfma_f32_32x32x16_bf16 v[2:17], v[190:193], v[198:201], v[2:17]
	s_waitcnt lgkmcnt(0)
; DI int crow(int reg, int h) { return (reg & 3) + 8 * (reg >> 2) + 4 * h; }
; template <typename Epi>
; DI void gemm_tile512(const u16* __restrict__ A, int lda, const u16* __restrict__ Bt, int ldb, int K, char* lds_all, Epi epi) {
;     ...
;     G5_COMPUTE(cur ^ 1);
;   }
; #pragma unroll 1
;   for (int half = 0; half < 2; ++half) {
;     __syncthreads();
;     if (wm == half) {
; #pragma unroll
;       for (int i = 0; i < 4; ++i)
; #pragma unroll
;         for (int j = 0; j < 2; ++j)
; #pragma unroll
;           for (int g = 0; g < 16; ++g) Cs[(i * 32 + crow(g, h)) * CSW + wn * 64 + j * 32 + r] = acc[i][j][g];
;     }
	v_mfma_f32_32x32x16_bf16 v[114:129], v[218:221], v[234:237], v[114:129]
	v_mfma_f32_32x32x16_bf16 v[98:113], v[218:221], v[202:205], v[98:113]
	v_mfma_f32_32x32x16_bf16 v[82:97], v[222:225], v[234:237], v[82:97]
	v_mfma_f32_32x32x16_bf16 v[66:81], v[222:225], v[202:205], v[66:81]
	v_mfma_f32_32x32x16_bf16 v[50:65], v[226:229], v[234:237], v[50:65]
	v_mfma_f32_32x32x16_bf16 v[34:49], v[226:229], v[202:205], v[34:49]
	v_mfma_f32_32x32x16_bf16 v[18:33], v[230:233], v[234:237], v[18:33]
	v_mfma_f32_32x32x16_bf16 v[2:17], v[230:233], v[202:205], v[2:17]
	v_mov_b32_e32 v210, 0xff
	v_mov_b32_e32 v211, 0xfff
	v_bfrev_b32_e32 v212, 4.0
	v_mov_b32_e32 v213, 0x1002
	v_mov_b32_e32 v240, 0x19860
	v_mov_b32_e32 v241, 0x1ad00
	v_mov_b32_e32 v242, 0x1b120
	v_mov_b32_e32 v243, 0x1b540
	v_mov_b32_e32 v190, 0x10c20
	v_mov_b32_e32 v191, 0x11040
	v_mov_b32_e32 v192, 0x11460
	v_mov_b32_e32 v193, 0x12900
	v_mov_b32_e32 v194, 0x12d20
	v_mov_b32_e32 v195, 0x13140
	v_mov_b32_e32 v196, 0x13560
	v_mov_b32_e32 v197, 0x14a00
	v_mov_b32_e32 v198, 0x14e20
	v_mov_b32_e32 v199, 0x15240
	v_mov_b32_e32 v200, 0x15660
	v_mov_b32_e32 v201, 0x16b00
	v_mov_b32_e32 v202, 0x16f20
	v_mov_b32_e32 v203, 0x17340
	v_mov_b32_e32 v204, 0x17760
	v_mov_b32_e32 v205, 0x18c00
	v_mov_b32_e32 v206, 0x19020
	v_mov_b32_e32 v207, 0x19440
	v_mov_b32_e32 v208, 0x10800
	v_lshrrev_b32_e32 v218, 8, v165
	v_bfe_u32 v219, v165, 5, 1
	v_and_b32_e32 v220, 31, v165
	v_bfe_u32 v221, v165, 6, 2
	s_mov_b32 s14, 0
	s_movk_i32 s10, 0x1080
	v_mov_b32_e32 v157, 0x1da60
	v_mad_u32_u24 v154, v219, s10, v245
	v_mad_u32_u24 v155, v219, s10, v246
	v_mad_u32_u24 v156, v219, s10, v247
	v_mad_u32_u24 v157, v219, s10, v157
	v_mov_b32_e32 v158, 0x1ef00
	v_mov_b32_e32 v159, 0x1f320
	v_mov_b32_e32 v160, 0x1f740
	v_mad_u32_u24 v158, v219, s10, v158
	v_mad_u32_u24 v159, v219, s10, v159
	v_mad_u32_u24 v160, v219, s10, v160
	v_lshlrev_b32_e32 v0, 8, v221
	v_mov_b32_e32 v166, 0x1fb60
	v_lshl_or_b32 v161, v220, 2, v0
	v_mad_u32_u24 v166, v219, s10, v166
	v_mad_u32_u24 v0, v219, s10, v161
	v_add_u32_e32 v154, v161, v154
	v_add_u32_e32 v155, v161, v155
	v_add_u32_e32 v156, v161, v156
	v_add_u32_e32 v157, v161, v157
	v_mad_u32_u24 v130, v219, s10, v208
	v_mad_u32_u24 v131, v219, s10, v190
	v_mad_u32_u24 v132, v219, s10, v191
	v_mad_u32_u24 v133, v219, s10, v192
	v_add_u32_e32 v130, v161, v130
	v_add_u32_e32 v131, v161, v131
	v_add_u32_e32 v132, v161, v132
	v_add_u32_e32 v133, v161, v133
	v_add_u32_e32 v158, v161, v158
	v_add_u32_e32 v159, v161, v159
	v_add_u32_e32 v160, v161, v160
	v_mad_u32_u24 v134, v219, s10, v193
	v_mad_u32_u24 v135, v219, s10, v194
	v_mad_u32_u24 v136, v219, s10, v195
	v_mad_u32_u24 v137, v219, s10, v196
	v_add_u32_e32 v134, v161, v134
	v_add_u32_e32 v135, v161, v135
	v_add_u32_e32 v136, v161, v136
	v_add_u32_e32 v137, v161, v137
	v_mad_u32_u24 v138, v219, s10, v197
	v_mad_u32_u24 v139, v219, s10, v198
	v_mad_u32_u24 v140, v219, s10, v199
	v_mad_u32_u24 v141, v219, s10, v200
	v_add_u32_e32 v138, v161, v138
	v_add_u32_e32 v139, v161, v139
	v_add_u32_e32 v140, v161, v140
	v_mad_u32_u24 v146, v219, s10, v205
	v_mad_u32_u24 v147, v219, s10, v206
	v_mad_u32_u24 v148, v219, s10, v207
	v_mad_u32_u24 v149, v219, s10, v240
	v_add_u32_e32 v141, v161, v141
	v_add_u32_e32 v146, v161, v146
	v_add_u32_e32 v147, v161, v147
	v_mad_u32_u24 v142, v219, s10, v201
	v_mad_u32_u24 v143, v219, s10, v202
	v_mad_u32_u24 v144, v219, s10, v203
	v_mad_u32_u24 v145, v219, s10, v204
	v_mad_u32_u24 v150, v219, s10, v241
	v_mad_u32_u24 v151, v219, s10, v242
	v_mad_u32_u24 v152, v219, s10, v243
	v_mad_u32_u24 v153, v219, s10, v244
	s_mov_b64 s[10:11], -1
	v_add_u32_e32 v142, v161, v142
	v_add_u32_e32 v143, v161, v143
	v_add_u32_e32 v144, v161, v144
	v_add_u32_e32 v145, v161, v145
	v_add_u32_e32 v148, v161, v148
	v_add_u32_e32 v149, v161, v149
	v_add_u32_e32 v150, v161, v150
	v_add_u32_e32 v151, v161, v151
	v_add_u32_e32 v152, v161, v152
	v_add_u32_e32 v153, v161, v153
	v_add_u32_e32 v161, v161, v166
	s_branch .LBB0_856
